# barrier: L1 invalidate issued together with the arrival atomic (every workgroup), so neither leader nor waiters pay it after the release
# speedup vs baseline: 1.0011x; 1.0011x over previous
; __device__ __forceinline__ unsigned xb_add(unsigned* p, unsigned v) { return __hip_atomic_fetch_add(p, v, __ATOMIC_RELAXED, __HIP_MEMORY_SCOPE_AGENT); }
; __device__ __forceinline__ void xcd_barrier(const XcdBarrier& b, bool tid0) {
;     ...
;     if (tid0) {
;         unsigned* bar = b.bar;
;         __builtin_amdgcn_s_waitcnt(0);
;         unsigned nloc = b.st[0], nx = b.st[1];
;         if (nloc == 0u) { xcd_barrier_complete(bar, b.x, b.G, nloc, nx); b.st[0] = nloc; b.st[1] = nx; }
;         const unsigned old = xb_add(&bar[XB_XSUB(b.x)], 1u);
;         const unsigned gen = old / nloc;
;         if (old + 1u == (gen + 1u) * nloc) {
.LBB0_187:
	s_lshl_b32 s6, s21, 8
	s_mov_b64 s[0:1], exec
	s_add_u32 s6, s4, s6
	s_addc_u32 s7, s5, 0
	v_mbcnt_lo_u32_b32 v1, s0, 0
	s_add_u32 s6, s6, 0x26120000
	v_mbcnt_hi_u32_b32 v1, s1, v1
	s_addc_u32 s7, s7, 0
	v_cmp_eq_u32_e32 vcc, 0, v1
	s_and_saveexec_b64 s[8:9], vcc
	s_cbranch_execz .LBB0_189
	s_bcnt1_i32_b64 s0, s[0:1]
	v_mov_b32_e32 v3, s0
	v_mov_b32_e32 v4, 0x1000
	global_atomic_add v3, v4, v3, s[6:7] offset:1024 sc0
	buffer_inv sc1

; __device__ __forceinline__ unsigned xb_ld(unsigned* p)              { return __hip_atomic_load(p, __ATOMIC_RELAXED, __HIP_MEMORY_SCOPE_AGENT); }
; __device__ __forceinline__ unsigned xb_add(unsigned* p, unsigned v) { return __hip_atomic_fetch_add(p, v, __ATOMIC_RELAXED, __HIP_MEMORY_SCOPE_AGENT); }
; #define XB_SPIN(cond, bar) do { unsigned _sp = 0; while (cond) { __builtin_amdgcn_s_sleep(1); \
;     if ((++_sp & 255u) == 0u) { if (xb_ld(&(bar)[XB_TMO])) break; if (_sp > XB_SPIN_CAP) { atomicAdd(&(bar)[XB_TMO], 1u); break; } } } } while (0)
; __device__ __forceinline__ void xcd_barrier(const XcdBarrier& b, bool tid0) {
;     ...
;             __builtin_amdgcn_fence(__ATOMIC_RELEASE, "agent");
;             asm volatile("s_waitcnt vmcnt(0)" ::: "memory");
;             const unsigned og = xb_add(&bar[XB_TOP], 1u);
;             const unsigned tg = og / nx;
;             if (og + 1u == (tg + 1u) * nx) xb_add(&bar[XB_TOPGEN], 1u);
;             else XB_SPIN(xb_ld(&bar[XB_TOPGEN]) == tg, bar);
;             __builtin_amdgcn_fence(__ATOMIC_ACQUIRE, "agent");
;             xb_add(&bar[XB_XGEN(b.x)], 1u);
;             asm volatile("s_waitcnt vmcnt(0)" ::: "memory");
;         } else {
;             XB_SPIN(xb_ld(&bar[XB_XGEN(b.x)]) == gen, bar);
;             __builtin_amdgcn_fence(__ATOMIC_ACQUIRE, "agent");
;             asm volatile("s_waitcnt vmcnt(0)" ::: "memory");
.LBB0_220:
	s_or_b64 exec, exec, s[4:5]
	s_mov_b64 s[0:1], exec
	v_mbcnt_lo_u32_b32 v0, s0, 0
	v_mbcnt_hi_u32_b32 v0, s1, v0
	v_cmp_eq_u32_e32 vcc, 0, v0
	s_waitcnt vmcnt(0)
	s_and_saveexec_b64 s[4:5], vcc
	s_cbranch_execz .LBB0_222
	s_bcnt1_i32_b64 s0, s[0:1]
	v_mov_b32_e32 v0, s0
	global_atomic_add v254, v0, s[6:7] offset:1024
.LBB0_222:
	s_or_b64 exec, exec, s[4:5]
	s_waitcnt vmcnt(0)
.LBB0_223:
	s_or_b64 exec, exec, s[2:3]
	s_cmp_eq_u32 s81, 0
	s_cbranch_scc1 .Lpf_skip_0
	s_load_dwordx2 vcc, s[78:79], 0xa0
	v_mbcnt_lo_u32_b32 v100, -1, 0
	v_mbcnt_hi_u32_b32 v100, -1, v100
	v_subrev_u32_e32 v100, s81, v100
	v_subrev_u32_e32 v100, 64, v100
	v_add_u32_e32 v103, 0x1c0, v100
	v_min_u32_e32 v103, 0x1ff, v103
	v_mov_b32_e32 v104, s75
	v_lshrrev_b32_e32 v104, 5, v104
	v_mov_b32_e32 v105, 0x200000
	v_mov_b32_e32 v101, s20
	v_lshrrev_b32_e32 v101, 1, v101
	v_mul_lo_u32 v105, v105, v101
	v_mov_b32_e32 v101, 0x40000
	v_mul_lo_u32 v104, v104, v101
	v_add_u32_e32 v104, v104, v105
	v_add_u32_e32 v104, 0x4000000, v104
	v_lshrrev_b32_e32 v101, 1, v100
	v_mov_b32_e32 v105, 0x400
	v_mul_lo_u32 v101, v101, v105
	v_and_b32_e32 v102, 1, v100
	v_lshl_add_u32 v101, v102, 7, v101
	v_add_u32_e32 v101, v101, v104
	v_lshrrev_b32_e32 v102, 1, v103
	v_mul_lo_u32 v102, v102, v105
	v_and_b32_e32 v103, 1, v103
	v_lshl_add_u32 v103, v103, 7, v102
	v_add_u32_e32 v103, v103, v104
	s_waitcnt lgkmcnt(0)
	global_load_dword v102, v101, vcc
	global_load_dword v104, v103, vcc

; __device__ __forceinline__ unsigned xb_add(unsigned* p, unsigned v) { return __hip_atomic_fetch_add(p, v, __ATOMIC_RELAXED, __HIP_MEMORY_SCOPE_AGENT); }
; __device__ __forceinline__ void xcd_barrier(const XcdBarrier& b, bool tid0) {
;     ...
;     if (tid0) {
;         unsigned* bar = b.bar;
;         __builtin_amdgcn_s_waitcnt(0);
;         unsigned nloc = b.st[0], nx = b.st[1];
;         if (nloc == 0u) { xcd_barrier_complete(bar, b.x, b.G, nloc, nx); b.st[0] = nloc; b.st[1] = nx; }
;         const unsigned old = xb_add(&bar[XB_XSUB(b.x)], 1u);
;         const unsigned gen = old / nloc;
;         if (old + 1u == (gen + 1u) * nloc) {
.LBB0_259:
	s_mov_b64 s[0:1], exec
	s_lshl_b32 s6, s19, 8
	v_mbcnt_lo_u32_b32 v1, s0, 0
	s_add_u32 s6, s4, s6
	v_mbcnt_hi_u32_b32 v1, s1, v1
	s_addc_u32 s7, s5, 0
	v_cmp_eq_u32_e32 vcc, 0, v1
	s_and_saveexec_b64 s[8:9], vcc
	s_cbranch_execz .LBB0_261
	s_bcnt1_i32_b64 s0, s[0:1]
	v_mov_b32_e32 v3, s0
	v_mov_b32_e32 v4, 0x1000
	global_atomic_add v3, v4, v3, s[6:7] offset:1024 sc0
	buffer_inv sc1

; __device__ __forceinline__ unsigned xb_ld(unsigned* p)              { return __hip_atomic_load(p, __ATOMIC_RELAXED, __HIP_MEMORY_SCOPE_AGENT); }
; __device__ __forceinline__ unsigned xb_add(unsigned* p, unsigned v) { return __hip_atomic_fetch_add(p, v, __ATOMIC_RELAXED, __HIP_MEMORY_SCOPE_AGENT); }
; #define XB_SPIN(cond, bar) do { unsigned _sp = 0; while (cond) { __builtin_amdgcn_s_sleep(1); \
;     if ((++_sp & 255u) == 0u) { if (xb_ld(&(bar)[XB_TMO])) break; if (_sp > XB_SPIN_CAP) { atomicAdd(&(bar)[XB_TMO], 1u); break; } } } } while (0)
; __device__ __forceinline__ void xcd_barrier(const XcdBarrier& b, bool tid0) {
;     ...
;             xb_add(&bar[XB_XGEN(b.x)], 1u);
;             asm volatile("s_waitcnt vmcnt(0)" ::: "memory");
;         } else {
;             XB_SPIN(xb_ld(&bar[XB_XGEN(b.x)]) == gen, bar);
;             __builtin_amdgcn_fence(__ATOMIC_ACQUIRE, "agent");
;             asm volatile("s_waitcnt vmcnt(0)" ::: "memory");
.Lfastbar_0:
	s_mov_b64 s[0:1], exec
	v_mbcnt_lo_u32_b32 v0, s0, 0
	v_mbcnt_hi_u32_b32 v0, s1, v0
	v_cmp_eq_u32_e32 vcc, 0, v0
	s_waitcnt vmcnt(0)
	s_and_saveexec_b64 s[4:5], vcc
	s_cbranch_execz .LBB0_294
	s_bcnt1_i32_b64 s0, s[0:1]
	v_mov_b32_e32 v0, s0
	global_atomic_add v254, v0, s[6:7] offset:1024
.LBB0_294:
	s_or_b64 exec, exec, s[4:5]
	s_waitcnt vmcnt(0)
.LBB0_295:
	s_or_b64 exec, exec, s[2:3]
	s_cmp_eq_u32 s81, 0
	s_cbranch_scc1 .Lpf_skip_2
	s_load_dwordx2 vcc, s[78:79], 0xa0
	v_mbcnt_lo_u32_b32 v100, -1, 0
	v_mbcnt_hi_u32_b32 v100, -1, v100
	v_subrev_u32_e32 v100, s81, v100
	v_subrev_u32_e32 v100, 64, v100
	v_add_u32_e32 v103, 0x1c0, v100
	v_min_u32_e32 v103, 0x1ff, v103
	v_mov_b32_e32 v104, s75
	v_lshrrev_b32_e32 v104, 5, v104
	v_mov_b32_e32 v105, 0x2c00000
	v_mul_lo_u32 v105, v105, s20
	v_mov_b32_e32 v101, 0x100000
	v_mul_lo_u32 v104, v104, v101
	v_add_u32_e32 v104, v104, v105
	v_add_u32_e32 v104, 0x4400000, v104
	v_lshrrev_b32_e32 v101, 1, v100
	v_mov_b32_e32 v105, 0x1000
	v_mul_lo_u32 v101, v101, v105
	v_and_b32_e32 v102, 1, v100
	v_lshl_add_u32 v101, v102, 7, v101
	v_add_u32_e32 v101, v101, v104
	v_lshrrev_b32_e32 v102, 1, v103
	v_mul_lo_u32 v102, v102, v105
	v_and_b32_e32 v103, 1, v103
	v_lshl_add_u32 v103, v103, 7, v102
	v_add_u32_e32 v103, v103, v104
	s_waitcnt lgkmcnt(0)
	global_load_dword v102, v101, vcc
	global_load_dword v104, v103, vcc

; __device__ __forceinline__ unsigned xb_ld(unsigned* p)              { return __hip_atomic_load(p, __ATOMIC_RELAXED, __HIP_MEMORY_SCOPE_AGENT); }
; __device__ __forceinline__ unsigned xb_add(unsigned* p, unsigned v) { return __hip_atomic_fetch_add(p, v, __ATOMIC_RELAXED, __HIP_MEMORY_SCOPE_AGENT); }
; #define XB_SPIN(cond, bar) do { unsigned _sp = 0; while (cond) { __builtin_amdgcn_s_sleep(1); \
;     if ((++_sp & 255u) == 0u) { if (xb_ld(&(bar)[XB_TMO])) break; if (_sp > XB_SPIN_CAP) { atomicAdd(&(bar)[XB_TMO], 1u); break; } } } } while (0)
; __device__ __forceinline__ void xcd_barrier(const XcdBarrier& b, bool tid0) {
;     ...
;             xb_add(&bar[XB_XGEN(b.x)], 1u);
;             asm volatile("s_waitcnt vmcnt(0)" ::: "memory");
;         } else {
;             XB_SPIN(xb_ld(&bar[XB_XGEN(b.x)]) == gen, bar);
;             __builtin_amdgcn_fence(__ATOMIC_ACQUIRE, "agent");
;             asm volatile("s_waitcnt vmcnt(0)" ::: "memory");
.LBB0_415:
	s_or_b64 exec, exec, s[4:5]
	s_mov_b64 s[0:1], exec
	v_mbcnt_lo_u32_b32 v0, s0, 0
	v_mbcnt_hi_u32_b32 v0, s1, v0
	v_cmp_eq_u32_e32 vcc, 0, v0
	s_waitcnt vmcnt(0)
	s_and_saveexec_b64 s[4:5], vcc
	s_cbranch_execz .LBB0_417
	s_bcnt1_i32_b64 s0, s[0:1]
	v_mov_b32_e32 v0, s0
	global_atomic_add v254, v0, s[6:7] offset:1024
.LBB0_417:
	s_or_b64 exec, exec, s[4:5]
	s_waitcnt vmcnt(0)

; __device__ __forceinline__ unsigned xb_add(unsigned* p, unsigned v) { return __hip_atomic_fetch_add(p, v, __ATOMIC_RELAXED, __HIP_MEMORY_SCOPE_AGENT); }
; __device__ __forceinline__ void xcd_barrier(const XcdBarrier& b, bool tid0) {
;     ...
;     if (tid0) {
;         unsigned* bar = b.bar;
;         __builtin_amdgcn_s_waitcnt(0);
;         unsigned nloc = b.st[0], nx = b.st[1];
;         if (nloc == 0u) { xcd_barrier_complete(bar, b.x, b.G, nloc, nx); b.st[0] = nloc; b.st[1] = nx; }
;         const unsigned old = xb_add(&bar[XB_XSUB(b.x)], 1u);
;         const unsigned gen = old / nloc;
;         if (old + 1u == (gen + 1u) * nloc) {
.LBB0_555:
	s_mov_b64 s[0:1], exec
	s_lshl_b32 s6, s21, 8
	v_mbcnt_lo_u32_b32 v1, s0, 0
	s_add_u32 s6, s4, s6
	v_mbcnt_hi_u32_b32 v1, s1, v1
	s_addc_u32 s7, s5, 0
	v_cmp_eq_u32_e32 vcc, 0, v1
	s_and_saveexec_b64 s[8:9], vcc
	s_cbranch_execz .LBB0_557
	s_bcnt1_i32_b64 s0, s[0:1]
	v_mov_b32_e32 v3, s0
	v_mov_b32_e32 v4, 0x1000
	global_atomic_add v3, v4, v3, s[6:7] offset:1024 sc0
	buffer_inv sc1

; __device__ __forceinline__ unsigned xb_ld(unsigned* p)              { return __hip_atomic_load(p, __ATOMIC_RELAXED, __HIP_MEMORY_SCOPE_AGENT); }
; __device__ __forceinline__ unsigned xb_add(unsigned* p, unsigned v) { return __hip_atomic_fetch_add(p, v, __ATOMIC_RELAXED, __HIP_MEMORY_SCOPE_AGENT); }
; #define XB_SPIN(cond, bar) do { unsigned _sp = 0; while (cond) { __builtin_amdgcn_s_sleep(1); \
;     if ((++_sp & 255u) == 0u) { if (xb_ld(&(bar)[XB_TMO])) break; if (_sp > XB_SPIN_CAP) { atomicAdd(&(bar)[XB_TMO], 1u); break; } } } } while (0)
; __device__ __forceinline__ void xcd_barrier(const XcdBarrier& b, bool tid0) {
;     ...
;             xb_add(&bar[XB_XGEN(b.x)], 1u);
;             asm volatile("s_waitcnt vmcnt(0)" ::: "memory");
;         } else {
;             XB_SPIN(xb_ld(&bar[XB_XGEN(b.x)]) == gen, bar);
;             __builtin_amdgcn_fence(__ATOMIC_ACQUIRE, "agent");
;             asm volatile("s_waitcnt vmcnt(0)" ::: "memory");
.Lfastbar_1:
	s_mov_b64 s[0:1], exec
	v_mbcnt_lo_u32_b32 v0, s0, 0
	v_mbcnt_hi_u32_b32 v0, s1, v0
	v_cmp_eq_u32_e32 vcc, 0, v0
	s_waitcnt vmcnt(0)
	s_and_saveexec_b64 s[4:5], vcc
	s_cbranch_execz .LBB0_590
	s_bcnt1_i32_b64 s0, s[0:1]
	v_mov_b32_e32 v0, s0
	global_atomic_add v254, v0, s[6:7] offset:1024
.LBB0_590:
	s_or_b64 exec, exec, s[4:5]
	s_waitcnt vmcnt(0)
.LBB0_591:
	s_or_b64 exec, exec, s[2:3]
	s_cmp_eq_u32 s81, 0
	s_cbranch_scc1 .Lpf_skip_1
	s_load_dwordx2 vcc, s[78:79], 0xa0
	v_mbcnt_lo_u32_b32 v100, -1, 0
	v_mbcnt_hi_u32_b32 v100, -1, v100
	v_subrev_u32_e32 v100, s81, v100
	v_subrev_u32_e32 v100, 64, v100
	v_add_u32_e32 v103, 0x1c0, v100
	v_min_u32_e32 v103, 0x1ff, v103
	v_mov_b32_e32 v104, s75
	v_lshrrev_b32_e32 v104, 5, v104
	v_mov_b32_e32 v105, 0x800000
	v_mov_b32_e32 v101, s20
	v_lshrrev_b32_e32 v101, 1, v101
	v_mul_lo_u32 v105, v105, v101
	v_mov_b32_e32 v101, 0x100000
	v_mul_lo_u32 v104, v104, v101
	v_add_u32_e32 v104, v104, v105
	v_add_u32_e32 v104, 0x3000000, v104
	v_lshrrev_b32_e32 v101, 1, v100
	v_mov_b32_e32 v105, 0x1000
	v_mul_lo_u32 v101, v101, v105
	v_and_b32_e32 v102, 1, v100
	v_lshl_add_u32 v101, v102, 7, v101
	v_add_u32_e32 v101, v101, v104
	v_lshrrev_b32_e32 v102, 1, v103
	v_mul_lo_u32 v102, v102, v105
	v_and_b32_e32 v103, 1, v103
	v_lshl_add_u32 v103, v103, 7, v102
	v_add_u32_e32 v103, v103, v104
	s_waitcnt lgkmcnt(0)
	global_load_dword v102, v101, vcc
	global_load_dword v104, v103, vcc

; __device__ __forceinline__ unsigned xb_ld(unsigned* p)              { return __hip_atomic_load(p, __ATOMIC_RELAXED, __HIP_MEMORY_SCOPE_AGENT); }
; __device__ __forceinline__ unsigned xb_add(unsigned* p, unsigned v) { return __hip_atomic_fetch_add(p, v, __ATOMIC_RELAXED, __HIP_MEMORY_SCOPE_AGENT); }
; #define XB_SPIN(cond, bar) do { unsigned _sp = 0; while (cond) { __builtin_amdgcn_s_sleep(1); \
;     if ((++_sp & 255u) == 0u) { if (xb_ld(&(bar)[XB_TMO])) break; if (_sp > XB_SPIN_CAP) { atomicAdd(&(bar)[XB_TMO], 1u); break; } } } } while (0)
; __device__ __forceinline__ void xcd_barrier(const XcdBarrier& b, bool tid0) {
;     ...
;             xb_add(&bar[XB_XGEN(b.x)], 1u);
;             asm volatile("s_waitcnt vmcnt(0)" ::: "memory");
;         } else {
;             XB_SPIN(xb_ld(&bar[XB_XGEN(b.x)]) == gen, bar);
;             __builtin_amdgcn_fence(__ATOMIC_ACQUIRE, "agent");
;             asm volatile("s_waitcnt vmcnt(0)" ::: "memory");
.Lfastbar_2:
	s_mov_b64 s[0:1], exec
	v_mbcnt_lo_u32_b32 v0, s0, 0
	v_mbcnt_hi_u32_b32 v0, s1, v0
	v_cmp_eq_u32_e32 vcc, 0, v0
	s_waitcnt vmcnt(0)
	s_and_saveexec_b64 s[4:5], vcc
	s_cbranch_execz .LBB0_658
	s_bcnt1_i32_b64 s0, s[0:1]
	v_mov_b32_e32 v0, s0
	global_atomic_add v254, v0, s[6:7] offset:1024
.LBB0_658:
	s_or_b64 exec, exec, s[4:5]
	s_waitcnt vmcnt(0)
.LBB0_659:
	s_or_b64 exec, exec, s[2:3]
	s_cmp_eq_u32 s81, 0
	s_cbranch_scc1 .Lpf_skip_3
	s_load_dwordx2 vcc, s[78:79], 0xa0
	v_mbcnt_lo_u32_b32 v100, -1, 0
	v_mbcnt_hi_u32_b32 v100, -1, v100
	v_subrev_u32_e32 v100, s81, v100
	v_subrev_u32_e32 v100, 64, v100
	v_add_u32_e32 v103, 0x1c0, v100
	v_min_u32_e32 v103, 0x1ff, v103
	v_mov_b32_e32 v104, s75
	v_lshrrev_b32_e32 v104, 5, v104
	v_mov_b32_e32 v105, 0x2c00000
	v_mul_lo_u32 v105, v105, s20
	v_mov_b32_e32 v101, 0x100000
	v_mul_lo_u32 v104, v104, v101
	v_add_u32_e32 v104, v104, v105
	v_add_u32_e32 v104, 0x4400000, v104
	v_lshrrev_b32_e32 v101, 1, v100
	v_mov_b32_e32 v105, 0x1000
	v_mul_lo_u32 v101, v101, v105
	v_and_b32_e32 v102, 1, v100
	v_lshl_add_u32 v101, v102, 7, v101
	v_add_u32_e32 v101, v101, v104
	v_lshrrev_b32_e32 v102, 1, v103
	v_mul_lo_u32 v102, v102, v105
	v_and_b32_e32 v103, 1, v103
	v_lshl_add_u32 v103, v103, 7, v102
	v_add_u32_e32 v103, v103, v104
	s_waitcnt lgkmcnt(0)
	global_load_dword v102, v101, vcc
	global_load_dword v104, v103, vcc

; __device__ __forceinline__ unsigned xb_add(unsigned* p, unsigned v) { return __hip_atomic_fetch_add(p, v, __ATOMIC_RELAXED, __HIP_MEMORY_SCOPE_AGENT); }
; __device__ __forceinline__ void xcd_barrier(const XcdBarrier& b, bool tid0) {
;     ...
;     if (tid0) {
;         unsigned* bar = b.bar;
;         __builtin_amdgcn_s_waitcnt(0);
;         unsigned nloc = b.st[0], nx = b.st[1];
;         if (nloc == 0u) { xcd_barrier_complete(bar, b.x, b.G, nloc, nx); b.st[0] = nloc; b.st[1] = nx; }
;         const unsigned old = xb_add(&bar[XB_XSUB(b.x)], 1u);
;         const unsigned gen = old / nloc;
;         if (old + 1u == (gen + 1u) * nloc) {
.LBB0_729:
	s_mov_b64 s[0:1], exec
	s_lshl_b32 s10, s30, 8
	v_mbcnt_lo_u32_b32 v1, s0, 0
	s_add_u32 s10, s8, s10
	v_mbcnt_hi_u32_b32 v1, s1, v1
	s_addc_u32 s11, s9, 0
	v_cmp_eq_u32_e32 vcc, 0, v1
	s_and_saveexec_b64 s[12:13], vcc
	s_cbranch_execz .LBB0_731
	s_bcnt1_i32_b64 s0, s[0:1]
	v_mov_b32_e32 v3, s0
	v_mov_b32_e32 v4, 0x1000
	global_atomic_add v3, v4, v3, s[10:11] offset:1024 sc0
	buffer_inv sc1

; __device__ __forceinline__ unsigned xb_ld(unsigned* p)              { return __hip_atomic_load(p, __ATOMIC_RELAXED, __HIP_MEMORY_SCOPE_AGENT); }
; __device__ __forceinline__ unsigned xb_add(unsigned* p, unsigned v) { return __hip_atomic_fetch_add(p, v, __ATOMIC_RELAXED, __HIP_MEMORY_SCOPE_AGENT); }
; #define XB_SPIN(cond, bar) do { unsigned _sp = 0; while (cond) { __builtin_amdgcn_s_sleep(1); \
;     if ((++_sp & 255u) == 0u) { if (xb_ld(&(bar)[XB_TMO])) break; if (_sp > XB_SPIN_CAP) { atomicAdd(&(bar)[XB_TMO], 1u); break; } } } } while (0)
; __device__ __forceinline__ void xcd_barrier(const XcdBarrier& b, bool tid0) {
;     ...
;             xb_add(&bar[XB_XGEN(b.x)], 1u);
;             asm volatile("s_waitcnt vmcnt(0)" ::: "memory");
;         } else {
;             XB_SPIN(xb_ld(&bar[XB_XGEN(b.x)]) == gen, bar);
;             __builtin_amdgcn_fence(__ATOMIC_ACQUIRE, "agent");
;             asm volatile("s_waitcnt vmcnt(0)" ::: "memory");
.Lfastbar_6:
	s_mov_b64 s[0:1], exec
	v_mbcnt_lo_u32_b32 v0, s0, 0
	v_mbcnt_hi_u32_b32 v0, s1, v0
	v_cmp_eq_u32_e32 vcc, 0, v0
	s_waitcnt vmcnt(0)
	s_and_saveexec_b64 s[8:9], vcc
	s_cbranch_execz .LBB0_764
	s_bcnt1_i32_b64 s0, s[0:1]
	v_mov_b32_e32 v0, s0
	global_atomic_add v254, v0, s[10:11] offset:1024
.LBB0_764:
	s_or_b64 exec, exec, s[8:9]
	s_waitcnt vmcnt(0)
.LBB0_765:
	s_or_b64 exec, exec, s[2:3]
	s_cmp_eq_u32 s81, 0
	s_cbranch_scc1 .Lpf_skip_4
	s_load_dwordx2 vcc, s[78:79], 0xa0
	v_mbcnt_lo_u32_b32 v100, -1, 0
	v_mbcnt_hi_u32_b32 v100, -1, v100
	v_subrev_u32_e32 v100, s81, v100
	v_subrev_u32_e32 v100, 64, v100
	v_add_u32_e32 v103, 0x1c0, v100
	v_min_u32_e32 v103, 0x1ff, v103
	v_mov_b32_e32 v104, s75
	v_lshrrev_b32_e32 v104, 5, v104
	v_mov_b32_e32 v105, 0x1600000
	v_mul_lo_u32 v105, v105, s20
	v_mov_b32_e32 v101, 0x2c0000
	v_mul_lo_u32 v104, v104, v101
	v_add_u32_e32 v104, v104, v105
	v_add_u32_e32 v104, 0xf400000, v104
	v_lshrrev_b32_e32 v101, 1, v100
	v_mov_b32_e32 v105, 0x2c00
	v_mul_lo_u32 v101, v101, v105
	v_and_b32_e32 v102, 1, v100
	v_lshl_add_u32 v101, v102, 7, v101
	v_add_u32_e32 v101, v101, v104
	v_lshrrev_b32_e32 v102, 1, v103
	v_mul_lo_u32 v102, v102, v105
	v_and_b32_e32 v103, 1, v103
	v_lshl_add_u32 v103, v103, 7, v102
	v_add_u32_e32 v103, v103, v104
	s_waitcnt lgkmcnt(0)
	global_load_dword v102, v101, vcc
	global_load_dword v104, v103, vcc

; __device__ __forceinline__ unsigned xb_add(unsigned* p, unsigned v) { return __hip_atomic_fetch_add(p, v, __ATOMIC_RELAXED, __HIP_MEMORY_SCOPE_AGENT); }
; __device__ __forceinline__ void xcd_barrier(const XcdBarrier& b, bool tid0) {
;     ...
;     if (tid0) {
;         unsigned* bar = b.bar;
;         __builtin_amdgcn_s_waitcnt(0);
;         unsigned nloc = b.st[0], nx = b.st[1];
;         if (nloc == 0u) { xcd_barrier_complete(bar, b.x, b.G, nloc, nx); b.st[0] = nloc; b.st[1] = nx; }
;         const unsigned old = xb_add(&bar[XB_XSUB(b.x)], 1u);
;         const unsigned gen = old / nloc;
;         if (old + 1u == (gen + 1u) * nloc) {
.LBB0_823:
	s_mov_b64 s[0:1], exec
	s_lshl_b32 s8, s28, 8
	v_mbcnt_lo_u32_b32 v1, s0, 0
	s_add_u32 s8, s6, s8
	v_mbcnt_hi_u32_b32 v1, s1, v1
	s_addc_u32 s9, s7, 0
	v_cmp_eq_u32_e32 vcc, 0, v1
	s_and_saveexec_b64 s[10:11], vcc
	s_cbranch_execz .LBB0_825
	s_bcnt1_i32_b64 s0, s[0:1]
	v_mov_b32_e32 v3, s0
	v_mov_b32_e32 v4, 0x1000
	global_atomic_add v3, v4, v3, s[8:9] offset:1024 sc0
	buffer_inv sc1

; __device__ __forceinline__ unsigned xb_ld(unsigned* p)              { return __hip_atomic_load(p, __ATOMIC_RELAXED, __HIP_MEMORY_SCOPE_AGENT); }
; __device__ __forceinline__ unsigned xb_add(unsigned* p, unsigned v) { return __hip_atomic_fetch_add(p, v, __ATOMIC_RELAXED, __HIP_MEMORY_SCOPE_AGENT); }
; #define XB_SPIN(cond, bar) do { unsigned _sp = 0; while (cond) { __builtin_amdgcn_s_sleep(1); \
;     if ((++_sp & 255u) == 0u) { if (xb_ld(&(bar)[XB_TMO])) break; if (_sp > XB_SPIN_CAP) { atomicAdd(&(bar)[XB_TMO], 1u); break; } } } } while (0)
; __device__ __forceinline__ void xcd_barrier(const XcdBarrier& b, bool tid0) {
;     ...
;             xb_add(&bar[XB_XGEN(b.x)], 1u);
;             asm volatile("s_waitcnt vmcnt(0)" ::: "memory");
;         } else {
;             XB_SPIN(xb_ld(&bar[XB_XGEN(b.x)]) == gen, bar);
;             __builtin_amdgcn_fence(__ATOMIC_ACQUIRE, "agent");
;             asm volatile("s_waitcnt vmcnt(0)" ::: "memory");
.Lfastbar_3:
	s_mov_b64 s[0:1], exec
	v_mbcnt_lo_u32_b32 v0, s0, 0
	v_mbcnt_hi_u32_b32 v0, s1, v0
	v_cmp_eq_u32_e32 vcc, 0, v0
	s_waitcnt vmcnt(0)
	s_and_saveexec_b64 s[6:7], vcc
	s_cbranch_execz .LBB0_858
	s_bcnt1_i32_b64 s0, s[0:1]
	v_mov_b32_e32 v0, s0
	global_atomic_add v254, v0, s[8:9] offset:1024
.LBB0_858:
	s_or_b64 exec, exec, s[6:7]
	s_waitcnt vmcnt(0)
.LBB0_859:
	s_or_b64 exec, exec, s[4:5]
	s_cmp_eq_u32 s81, 0
	s_cbranch_scc1 .Lpf_skip_5
	s_load_dwordx2 vcc, s[78:79], 0xa0
	v_mbcnt_lo_u32_b32 v100, -1, 0
	v_mbcnt_hi_u32_b32 v100, -1, v100
	v_subrev_u32_e32 v100, s81, v100
	v_subrev_u32_e32 v100, 64, v100
	v_add_u32_e32 v103, 0x1c0, v100
	v_min_u32_e32 v103, 0x1ff, v103
	v_mov_b32_e32 v104, s75
	v_lshrrev_b32_e32 v104, 5, v104
	v_mov_b32_e32 v105, 0x800000
	v_mul_lo_u32 v105, v105, s20
	v_mov_b32_e32 v101, 0x100000
	v_mul_lo_u32 v104, v104, v101
	v_add_u32_e32 v104, v104, v105
	v_add_u32_e32 v104, 0x14c00000, v104
	v_lshrrev_b32_e32 v101, 1, v100
	v_mov_b32_e32 v105, 0x1000
	v_mul_lo_u32 v101, v101, v105
	v_and_b32_e32 v102, 1, v100
	v_lshl_add_u32 v101, v102, 7, v101
	v_add_u32_e32 v101, v101, v104
	v_lshrrev_b32_e32 v102, 1, v103
	v_mul_lo_u32 v102, v102, v105
	v_and_b32_e32 v103, 1, v103
	v_lshl_add_u32 v103, v103, 7, v102
	v_add_u32_e32 v103, v103, v104
	s_waitcnt lgkmcnt(0)
	global_load_dword v102, v101, vcc
	global_load_dword v104, v103, vcc

; __device__ __forceinline__ unsigned xb_add(unsigned* p, unsigned v) { return __hip_atomic_fetch_add(p, v, __ATOMIC_RELAXED, __HIP_MEMORY_SCOPE_AGENT); }
; __device__ __forceinline__ void xcd_barrier(const XcdBarrier& b, bool tid0) {
;     ...
;     if (tid0) {
;         unsigned* bar = b.bar;
;         __builtin_amdgcn_s_waitcnt(0);
;         unsigned nloc = b.st[0], nx = b.st[1];
;         if (nloc == 0u) { xcd_barrier_complete(bar, b.x, b.G, nloc, nx); b.st[0] = nloc; b.st[1] = nx; }
;         const unsigned old = xb_add(&bar[XB_XSUB(b.x)], 1u);
;         const unsigned gen = old / nloc;
;         if (old + 1u == (gen + 1u) * nloc) {
.LBB0_894:
	s_mov_b64 s[0:1], exec
	s_lshl_b32 s6, s18, 8
	v_mbcnt_lo_u32_b32 v1, s0, 0
	s_add_u32 s6, s4, s6
	v_mbcnt_hi_u32_b32 v1, s1, v1
	s_addc_u32 s7, s5, 0
	v_cmp_eq_u32_e32 vcc, 0, v1
	s_and_saveexec_b64 s[8:9], vcc
	s_cbranch_execz .LBB0_896
	s_bcnt1_i32_b64 s0, s[0:1]
	v_mov_b32_e32 v3, s0
	v_mov_b32_e32 v4, 0x1000
	global_atomic_add v3, v4, v3, s[6:7] offset:1024 sc0
	buffer_inv sc1

; __device__ __forceinline__ unsigned xb_ld(unsigned* p)              { return __hip_atomic_load(p, __ATOMIC_RELAXED, __HIP_MEMORY_SCOPE_AGENT); }
; __device__ __forceinline__ unsigned xb_add(unsigned* p, unsigned v) { return __hip_atomic_fetch_add(p, v, __ATOMIC_RELAXED, __HIP_MEMORY_SCOPE_AGENT); }
; #define XB_SPIN(cond, bar) do { unsigned _sp = 0; while (cond) { __builtin_amdgcn_s_sleep(1); \
;     if ((++_sp & 255u) == 0u) { if (xb_ld(&(bar)[XB_TMO])) break; if (_sp > XB_SPIN_CAP) { atomicAdd(&(bar)[XB_TMO], 1u); break; } } } } while (0)
; __device__ __forceinline__ void xcd_barrier(const XcdBarrier& b, bool tid0) {
;     ...
;             xb_add(&bar[XB_XGEN(b.x)], 1u);
;             asm volatile("s_waitcnt vmcnt(0)" ::: "memory");
;         } else {
;             XB_SPIN(xb_ld(&bar[XB_XGEN(b.x)]) == gen, bar);
;             __builtin_amdgcn_fence(__ATOMIC_ACQUIRE, "agent");
;             asm volatile("s_waitcnt vmcnt(0)" ::: "memory");
.Lfastbar_4:
	s_mov_b64 s[0:1], exec
	v_mbcnt_lo_u32_b32 v0, s0, 0
	v_mbcnt_hi_u32_b32 v0, s1, v0
	v_cmp_eq_u32_e32 vcc, 0, v0
	s_waitcnt vmcnt(0)
	s_and_saveexec_b64 s[4:5], vcc
	s_cbranch_execz .LBB0_929
	s_bcnt1_i32_b64 s0, s[0:1]
	v_mov_b32_e32 v0, s0
	global_atomic_add v254, v0, s[6:7] offset:1024
.LBB0_929:
	s_or_b64 exec, exec, s[4:5]
	s_waitcnt vmcnt(0)

; __device__ __forceinline__ unsigned xb_add(unsigned* p, unsigned v) { return __hip_atomic_fetch_add(p, v, __ATOMIC_RELAXED, __HIP_MEMORY_SCOPE_AGENT); }
; __device__ __forceinline__ void xcd_barrier(const XcdBarrier& b, bool tid0) {
;     ...
;     if (tid0) {
;         unsigned* bar = b.bar;
;         __builtin_amdgcn_s_waitcnt(0);
;         unsigned nloc = b.st[0], nx = b.st[1];
;         if (nloc == 0u) { xcd_barrier_complete(bar, b.x, b.G, nloc, nx); b.st[0] = nloc; b.st[1] = nx; }
;         const unsigned old = xb_add(&bar[XB_XSUB(b.x)], 1u);
;         const unsigned gen = old / nloc;
;         if (old + 1u == (gen + 1u) * nloc) {
.LBB0_947:
	s_lshl_b32 s6, s41, 8
	s_mov_b64 s[0:1], exec
	s_add_u32 s6, s4, s6
	s_addc_u32 s7, s5, 0
	v_mbcnt_lo_u32_b32 v1, s0, 0
	s_add_u32 s6, s6, 0x26120000
	v_mbcnt_hi_u32_b32 v1, s1, v1
	s_addc_u32 s7, s7, 0
	v_cmp_eq_u32_e32 vcc, 0, v1
	s_and_saveexec_b64 s[8:9], vcc
	s_cbranch_execz .LBB0_949
	s_bcnt1_i32_b64 s0, s[0:1]
	v_mov_b32_e32 v3, s0
	v_mov_b32_e32 v4, 0x1000
	global_atomic_add v3, v4, v3, s[6:7] offset:1024 sc0
	buffer_inv sc1

; __device__ __forceinline__ unsigned xb_ld(unsigned* p)              { return __hip_atomic_load(p, __ATOMIC_RELAXED, __HIP_MEMORY_SCOPE_AGENT); }
; __device__ __forceinline__ unsigned xb_add(unsigned* p, unsigned v) { return __hip_atomic_fetch_add(p, v, __ATOMIC_RELAXED, __HIP_MEMORY_SCOPE_AGENT); }
; #define XB_SPIN(cond, bar) do { unsigned _sp = 0; while (cond) { __builtin_amdgcn_s_sleep(1); \
;     if ((++_sp & 255u) == 0u) { if (xb_ld(&(bar)[XB_TMO])) break; if (_sp > XB_SPIN_CAP) { atomicAdd(&(bar)[XB_TMO], 1u); break; } } } } while (0)
; __device__ __forceinline__ void xcd_barrier(const XcdBarrier& b, bool tid0) {
;     ...
;             xb_add(&bar[XB_XGEN(b.x)], 1u);
;             asm volatile("s_waitcnt vmcnt(0)" ::: "memory");
;         } else {
;             XB_SPIN(xb_ld(&bar[XB_XGEN(b.x)]) == gen, bar);
;             __builtin_amdgcn_fence(__ATOMIC_ACQUIRE, "agent");
;             asm volatile("s_waitcnt vmcnt(0)" ::: "memory");
.LBB0_980:
	s_or_b64 exec, exec, s[4:5]
	s_mov_b64 s[0:1], exec
	v_mbcnt_lo_u32_b32 v0, s0, 0
	v_mbcnt_hi_u32_b32 v0, s1, v0
	v_cmp_eq_u32_e32 vcc, 0, v0
	s_waitcnt vmcnt(0)
	s_and_saveexec_b64 s[4:5], vcc
	s_cbranch_execz .LBB0_982
	s_bcnt1_i32_b64 s0, s[0:1]
	v_mov_b32_e32 v0, s0
	global_atomic_add v254, v0, s[6:7] offset:1024
.LBB0_982:
	s_or_b64 exec, exec, s[4:5]
	s_waitcnt vmcnt(0)

; __device__ __forceinline__ unsigned xb_add(unsigned* p, unsigned v) { return __hip_atomic_fetch_add(p, v, __ATOMIC_RELAXED, __HIP_MEMORY_SCOPE_AGENT); }
; __device__ __forceinline__ void xcd_barrier(const XcdBarrier& b, bool tid0) {
;     ...
;     if (tid0) {
;         unsigned* bar = b.bar;
;         __builtin_amdgcn_s_waitcnt(0);
;         unsigned nloc = b.st[0], nx = b.st[1];
;         if (nloc == 0u) { xcd_barrier_complete(bar, b.x, b.G, nloc, nx); b.st[0] = nloc; b.st[1] = nx; }
;         const unsigned old = xb_add(&bar[XB_XSUB(b.x)], 1u);
;         const unsigned gen = old / nloc;
;         if (old + 1u == (gen + 1u) * nloc) {
.LBB0_1014:
	s_mov_b64 s[4:5], exec
	v_mbcnt_lo_u32_b32 v1, s4, 0
	v_mbcnt_hi_u32_b32 v1, s5, v1
	v_cmp_eq_u32_e32 vcc, 0, v1
	s_and_saveexec_b64 s[0:1], vcc
	s_cbranch_execz .LBB0_1016
	s_bcnt1_i32_b64 s4, s[4:5]
	v_mov_b32_e32 v3, s4
	global_atomic_add v3, v177, v3, s[48:49] sc0
	buffer_inv sc1

; __device__ __forceinline__ unsigned xb_ld(unsigned* p)              { return __hip_atomic_load(p, __ATOMIC_RELAXED, __HIP_MEMORY_SCOPE_AGENT); }
; __device__ __forceinline__ unsigned xb_add(unsigned* p, unsigned v) { return __hip_atomic_fetch_add(p, v, __ATOMIC_RELAXED, __HIP_MEMORY_SCOPE_AGENT); }
; #define XB_SPIN(cond, bar) do { unsigned _sp = 0; while (cond) { __builtin_amdgcn_s_sleep(1); \
;     if ((++_sp & 255u) == 0u) { if (xb_ld(&(bar)[XB_TMO])) break; if (_sp > XB_SPIN_CAP) { atomicAdd(&(bar)[XB_TMO], 1u); break; } } } } while (0)
; __device__ __forceinline__ void xcd_barrier(const XcdBarrier& b, bool tid0) {
;     ...
;             xb_add(&bar[XB_XGEN(b.x)], 1u);
;             asm volatile("s_waitcnt vmcnt(0)" ::: "memory");
;         } else {
;             XB_SPIN(xb_ld(&bar[XB_XGEN(b.x)]) == gen, bar);
;             __builtin_amdgcn_fence(__ATOMIC_ACQUIRE, "agent");
;             asm volatile("s_waitcnt vmcnt(0)" ::: "memory");
.Lfastbar_5:
	s_mov_b64 s[0:1], exec
	v_mbcnt_lo_u32_b32 v0, s0, 0
	v_mbcnt_hi_u32_b32 v0, s1, v0
	v_cmp_eq_u32_e32 vcc, 0, v0
	s_waitcnt vmcnt(0)
	s_and_saveexec_b64 s[4:5], vcc
	s_cbranch_execz .LBB0_1049
	s_bcnt1_i32_b64 s0, s[0:1]
	v_mov_b32_e32 v0, s0
	global_atomic_add v177, v0, s[52:53]
.LBB0_1049:
	s_or_b64 exec, exec, s[4:5]
	s_waitcnt vmcnt(0)
